# v18 with nt kept only on the dwordx4 bulk loads of P0 / P3 conversions (dword and dwordx2 loads, i.e. vectors and small shared data, stay temporal)
# speedup vs baseline: 1.0049x; 1.0009x over previous
; #define LAS __attribute__((address_space(3)))
; __device__ __forceinline__ void p0_transpose_item64(const WsRef& wsr, const float* W, int K, int N, bf16* WT, LAS float* scr, int item, int lane, const float* kscale = nullptr) {
;     ...
;     for (int i = 0; i < 16; ++i) v[i] = *(const f32x4*)(W + (size_t)(k0 + 4 * i + kq) * N + n0 + nq * 4);
; #pragma unroll
;     for (int i = 0; i < 16; ++i) { const int kk = 4 * i + kq; const float sc = kscale ? kscale[k0 + kk] : 1.0f; LAS float* d = scr + kk * 65 + nq * 4;
;         d[0] = v[i][0] * sc; d[1] = v[i][1] * sc; d[2] = v[i][2] * sc; d[3] = v[i][3] * sc; }
.LBB0_24:
	s_andn2_b64 vcc, exec, s[0:1]
	s_cbranch_vccnz .LBB0_21
	s_mul_hi_i32 s0, s55, 0x2aaaaaab
	s_lshr_b32 s1, s0, 31
	s_ashr_i32 s0, s0, 3
	s_add_i32 s0, s0, s1
	s_lshl_b32 s34, s0, 6
	s_mulk_i32 s0, 0xf400
	s_add_i32 s30, s3, s0
	v_or_b32_e32 v76, s34, v64
	s_ashr_i32 s31, s30, 31
	v_lshl_add_u64 v[0:1], s[30:31], 2, v[72:73]
	v_or_b32_e32 v4, 4, v76
	v_mad_i64_i32 v[2:3], s[0:1], v76, s54, v[0:1]
	v_mad_i64_i32 v[4:5], s[0:1], v4, s54, v[0:1]
	global_load_dwordx4 v[60:63], v[2:3], off nt
	global_load_dwordx4 v[56:59], v[4:5], off nt
	v_or_b32_e32 v2, 8, v76
	v_or_b32_e32 v4, 12, v76
	v_mad_i64_i32 v[2:3], s[0:1], v2, s54, v[0:1]
	v_mad_i64_i32 v[4:5], s[0:1], v4, s54, v[0:1]
	global_load_dwordx4 v[52:55], v[2:3], off nt
	global_load_dwordx4 v[48:51], v[4:5], off nt
	v_or_b32_e32 v2, 16, v76
	v_or_b32_e32 v4, 20, v76
	v_mad_i64_i32 v[2:3], s[0:1], v2, s54, v[0:1]
	v_mad_i64_i32 v[4:5], s[0:1], v4, s54, v[0:1]
	global_load_dwordx4 v[44:47], v[2:3], off nt
	global_load_dwordx4 v[40:43], v[4:5], off nt
	v_or_b32_e32 v2, 24, v76
	v_or_b32_e32 v4, 28, v76
	v_mad_i64_i32 v[2:3], s[0:1], v2, s54, v[0:1]
	v_mad_i64_i32 v[4:5], s[0:1], v4, s54, v[0:1]
	global_load_dwordx4 v[36:39], v[2:3], off nt
	global_load_dwordx4 v[32:35], v[4:5], off nt
	v_or_b32_e32 v2, 32, v76
	v_or_b32_e32 v4, 36, v76
	v_mad_i64_i32 v[2:3], s[0:1], v2, s54, v[0:1]
	v_mad_i64_i32 v[4:5], s[0:1], v4, s54, v[0:1]
	v_or_b32_e32 v10, 56, v76
	global_load_dwordx4 v[28:31], v[2:3], off nt
	global_load_dwordx4 v[24:27], v[4:5], off nt
	v_or_b32_e32 v2, 40, v76
	v_or_b32_e32 v4, 44, v76
	v_or_b32_e32 v6, 48, v76
	v_or_b32_e32 v8, 52, v76
	v_mad_i64_i32 v[118:119], s[0:1], v10, s54, v[0:1]
	v_or_b32_e32 v10, 60, v76
	v_mad_i64_i32 v[2:3], s[0:1], v2, s54, v[0:1]
	v_mad_i64_i32 v[4:5], s[0:1], v4, s54, v[0:1]
	v_mad_i64_i32 v[6:7], s[0:1], v6, s54, v[0:1]
	v_mad_i64_i32 v[8:9], s[0:1], v8, s54, v[0:1]
	v_mad_i64_i32 v[0:1], s[0:1], v10, s54, v[0:1]
	global_load_dwordx4 v[20:23], v[2:3], off nt
	global_load_dwordx4 v[16:19], v[4:5], off nt
	global_load_dwordx4 v[12:15], v[6:7], off nt
	s_nop 0
	global_load_dwordx4 v[8:11], v[8:9], off nt
	s_nop 0
	global_load_dwordx4 v[4:7], v[118:119], off nt
	s_nop 0
	global_load_dwordx4 v[0:3], v[0:1], off nt
	v_cndmask_b32_e64 v66, 0, 1, s[16:17]
	v_cmp_ne_u32_e64 s[0:1], 1, v66
	s_andn2_b64 vcc, exec, s[16:17]
	s_cbranch_vccnz .LBB0_48
	v_ashrrev_i32_e32 v77, 31, v76
	s_ashr_i32 s35, s34, 31
	v_lshl_add_u64 v[76:77], v[76:77], 2, s[14:15]
	v_lshl_add_u64 v[118:119], s[34:35], 0, v[64:65]
	global_load_dword v76, v[76:77], off
	v_lshl_add_u64 v[118:119], v[118:119], 2, s[14:15]
	global_load_dword v66, v[118:119], off offset:16
	s_waitcnt vmcnt(1)
	v_pk_mul_f32 v[118:119], v[60:61], v[76:77] op_sel_hi:[1,0]
	v_pk_mul_f32 v[76:77], v[62:63], v[76:77] op_sel_hi:[1,0]
	ds_write2_b32 v75, v118, v119 offset1:1
	ds_write2_b32 v75, v76, v77 offset0:2 offset1:3
	s_cbranch_execnz .LBB0_28

; #define LAS __attribute__((address_space(3)))
; __device__ __forceinline__ void p0_transpose_item64(const WsRef& wsr, const float* W, int K, int N, bf16* WT, LAS float* scr, int item, int lane, const float* kscale = nullptr) {
;     ...
;     for (int i = 0; i < 16; ++i) v[i] = *(const f32x4*)(W + (size_t)(k0 + 4 * i + kq) * N + n0 + nq * 4);
; #pragma unroll
;     for (int i = 0; i < 16; ++i) { const int kk = 4 * i + kq; const float sc = kscale ? kscale[k0 + kk] : 1.0f; LAS float* d = scr + kk * 65 + nq * 4;
;         d[0] = v[i][0] * sc; d[1] = v[i][1] * sc; d[2] = v[i][2] * sc; d[3] = v[i][3] * sc; }
.LBB0_300:
	s_andn2_b64 vcc, exec, s[0:1]
	s_cbranch_vccnz .LBB0_326
	s_add_i32 s0, s34, 0xfd00
	s_and_b32 s38, s0, 0xffc0
	s_and_b32 s35, s3, 0xfc0
	v_or_b32_e32 v114, s38, v86
	s_lshl_b32 s8, s35, 2
	v_lshl_add_u64 v[0:1], v[70:71], 0, s[8:9]
	v_lshlrev_b32_e32 v64, 14, v114
	v_lshl_add_u64 v[0:1], v[0:1], 0, v[64:65]
	v_add_co_u32_e32 v2, vcc, 0x10000, v0
	v_cndmask_b32_e64 v64, 0, 1, s[10:11]
	s_nop 0
	v_addc_co_u32_e32 v3, vcc, 0, v1, vcc
	global_load_dwordx4 v[60:63], v[0:1], off nt
	global_load_dwordx4 v[56:59], v[2:3], off nt
	v_add_co_u32_e32 v2, vcc, 0x20000, v0
	v_cmp_ne_u32_e64 s[0:1], 1, v64
	s_nop 0
	v_addc_co_u32_e32 v3, vcc, 0, v1, vcc
	v_add_co_u32_e32 v4, vcc, 0x30000, v0
	v_add_lshl_u32 v113, s38, v86, 2
	s_nop 0
	v_addc_co_u32_e32 v5, vcc, 0, v1, vcc
	global_load_dwordx4 v[52:55], v[2:3], off nt
	global_load_dwordx4 v[48:51], v[4:5], off nt
	v_add_co_u32_e32 v2, vcc, 0x40000, v0
	s_nop 1
	v_addc_co_u32_e32 v3, vcc, 0, v1, vcc
	v_add_co_u32_e32 v4, vcc, 0x50000, v0
	s_nop 1
	v_addc_co_u32_e32 v5, vcc, 0, v1, vcc
	global_load_dwordx4 v[44:47], v[2:3], off nt
	global_load_dwordx4 v[40:43], v[4:5], off nt
	v_add_co_u32_e32 v2, vcc, 0x60000, v0
	s_nop 1
	v_addc_co_u32_e32 v3, vcc, 0, v1, vcc
	v_add_co_u32_e32 v4, vcc, 0x70000, v0
	s_nop 1
	v_addc_co_u32_e32 v5, vcc, 0, v1, vcc
	global_load_dwordx4 v[36:39], v[2:3], off nt
	global_load_dwordx4 v[32:35], v[4:5], off nt
	v_add_co_u32_e32 v2, vcc, 0x80000, v0
	s_nop 1
	v_addc_co_u32_e32 v3, vcc, 0, v1, vcc
	v_add_co_u32_e32 v4, vcc, 0x90000, v0
	s_nop 1
	v_addc_co_u32_e32 v5, vcc, 0, v1, vcc
	global_load_dwordx4 v[28:31], v[2:3], off nt
	global_load_dwordx4 v[24:27], v[4:5], off nt
	v_add_co_u32_e32 v2, vcc, 0xa0000, v0
	s_nop 1
	v_addc_co_u32_e32 v3, vcc, 0, v1, vcc
	v_add_co_u32_e32 v4, vcc, 0xb0000, v0
	s_nop 1
	v_addc_co_u32_e32 v5, vcc, 0, v1, vcc
	global_load_dwordx4 v[20:23], v[2:3], off nt
	global_load_dwordx4 v[16:19], v[4:5], off nt
	v_add_co_u32_e32 v2, vcc, 0xc0000, v0
	s_nop 1
	v_addc_co_u32_e32 v3, vcc, 0, v1, vcc
	v_add_co_u32_e32 v4, vcc, 0xd0000, v0
	s_nop 1
	v_addc_co_u32_e32 v5, vcc, 0, v1, vcc
	global_load_dwordx4 v[12:15], v[2:3], off nt
	global_load_dwordx4 v[8:11], v[4:5], off nt
	v_add_co_u32_e32 v2, vcc, 0xe0000, v0
	s_nop 1
	v_addc_co_u32_e32 v3, vcc, 0, v1, vcc
	v_add_co_u32_e32 v0, vcc, 0xf0000, v0
	s_nop 1
	v_addc_co_u32_e32 v1, vcc, 0, v1, vcc
	global_load_dwordx4 v[4:7], v[2:3], off nt
	s_nop 0
	global_load_dwordx4 v[0:3], v[0:1], off nt
	s_andn2_b64 vcc, exec, s[10:11]
	s_cbranch_vccnz .LBB0_367
	v_readlane_b32 s52, v255, 10
	v_lshlrev_b32_e32 v64, 2, v114
	v_readlane_b32 s58, v255, 16
	v_readlane_b32 s59, v255, 17
	s_nop 4
	global_load_dword v114, v64, s[58:59]
	s_nop 0
	global_load_dword v64, v113, s[58:59] offset:16
	v_readlane_b32 s53, v255, 11
	v_readlane_b32 s54, v255, 12
	v_readlane_b32 s55, v255, 13
	v_readlane_b32 s56, v255, 14
	v_readlane_b32 s57, v255, 15
	v_readlane_b32 s60, v255, 18
	v_readlane_b32 s61, v255, 19
	v_readlane_b32 s62, v255, 20
	v_readlane_b32 s63, v255, 21
	v_readlane_b32 s64, v255, 22
	v_readlane_b32 s65, v255, 23
	v_readlane_b32 s66, v255, 24
	v_readlane_b32 s67, v255, 25
	s_waitcnt vmcnt(0)
	v_pk_mul_f32 v[116:117], v[60:61], v[114:115] op_sel_hi:[1,0]
	v_pk_mul_f32 v[114:115], v[62:63], v[114:115] op_sel_hi:[1,0]
	ds_write2_b32 v88, v116, v117 offset1:1
	ds_write2_b32 v88, v114, v115 offset0:2 offset1:3
	s_cbranch_execnz .LBB0_304

; #define LAS __attribute__((address_space(3)))
; __device__ __forceinline__ void p0_transpose_item64(const WsRef& wsr, const float* W, int K, int N, bf16* WT, LAS float* scr, int item, int lane, const float* kscale = nullptr) {
;     ...
;     for (int i = 0; i < 16; ++i) v[i] = *(const f32x4*)(W + (size_t)(k0 + 4 * i + kq) * N + n0 + nq * 4);
; #pragma unroll
;     for (int i = 0; i < 16; ++i) { const int kk = 4 * i + kq; const float sc = kscale ? kscale[k0 + kk] : 1.0f; LAS float* d = scr + kk * 65 + nq * 4;
;         d[0] = v[i][0] * sc; d[1] = v[i][1] * sc; d[2] = v[i][2] * sc; d[3] = v[i][3] * sc; }
.LBB0_330:
	s_andn2_b64 vcc, exec, s[0:1]
	s_cbranch_vccnz .LBB0_356
	s_and_b32 s38, s31, 0x3c0
	s_and_b32 s35, s3, 0x3c0
	v_or_b32_e32 v114, s38, v86
	s_lshl_b32 s8, s35, 2
	v_lshl_add_u64 v[0:1], v[78:79], 0, s[8:9]
	v_lshlrev_b32_e32 v64, 12, v114
	v_lshl_add_u64 v[0:1], v[0:1], 0, v[64:65]
	v_add_co_u32_e32 v2, vcc, 0x4000, v0
	v_cndmask_b32_e64 v64, 0, 1, s[26:27]
	s_nop 0
	v_addc_co_u32_e32 v3, vcc, 0, v1, vcc
	global_load_dwordx4 v[60:63], v[0:1], off nt
	global_load_dwordx4 v[56:59], v[2:3], off nt
	v_add_co_u32_e32 v2, vcc, 0x8000, v0
	v_cmp_ne_u32_e64 s[0:1], 1, v64
	s_nop 0
	v_addc_co_u32_e32 v3, vcc, 0, v1, vcc
	v_add_co_u32_e32 v4, vcc, 0xc000, v0
	v_add_lshl_u32 v113, s38, v86, 2
	s_nop 0
	v_addc_co_u32_e32 v5, vcc, 0, v1, vcc
	global_load_dwordx4 v[52:55], v[2:3], off nt
	global_load_dwordx4 v[48:51], v[4:5], off nt
	v_add_co_u32_e32 v2, vcc, 0x10000, v0
	s_nop 1
	v_addc_co_u32_e32 v3, vcc, 0, v1, vcc
	v_add_co_u32_e32 v4, vcc, 0x14000, v0
	s_nop 1
	v_addc_co_u32_e32 v5, vcc, 0, v1, vcc
	global_load_dwordx4 v[44:47], v[2:3], off nt
	global_load_dwordx4 v[40:43], v[4:5], off nt
	v_add_co_u32_e32 v2, vcc, 0x18000, v0
	s_nop 1
	v_addc_co_u32_e32 v3, vcc, 0, v1, vcc
	v_add_co_u32_e32 v4, vcc, 0x1c000, v0
	s_nop 1
	v_addc_co_u32_e32 v5, vcc, 0, v1, vcc
	global_load_dwordx4 v[36:39], v[2:3], off nt
	global_load_dwordx4 v[32:35], v[4:5], off nt
	v_add_co_u32_e32 v2, vcc, 0x20000, v0
	s_nop 1
	v_addc_co_u32_e32 v3, vcc, 0, v1, vcc
	v_add_co_u32_e32 v4, vcc, 0x24000, v0
	s_nop 1
	v_addc_co_u32_e32 v5, vcc, 0, v1, vcc
	global_load_dwordx4 v[28:31], v[2:3], off nt
	global_load_dwordx4 v[24:27], v[4:5], off nt
	v_add_co_u32_e32 v2, vcc, 0x28000, v0
	s_nop 1
	v_addc_co_u32_e32 v3, vcc, 0, v1, vcc
	v_add_co_u32_e32 v4, vcc, 0x2c000, v0
	s_nop 1
	v_addc_co_u32_e32 v5, vcc, 0, v1, vcc
	global_load_dwordx4 v[20:23], v[2:3], off nt
	global_load_dwordx4 v[16:19], v[4:5], off nt
	v_add_co_u32_e32 v2, vcc, 0x30000, v0
	s_nop 1
	v_addc_co_u32_e32 v3, vcc, 0, v1, vcc
	v_add_co_u32_e32 v4, vcc, 0x34000, v0
	s_nop 1
	v_addc_co_u32_e32 v5, vcc, 0, v1, vcc
	global_load_dwordx4 v[12:15], v[2:3], off nt
	global_load_dwordx4 v[8:11], v[4:5], off nt
	v_add_co_u32_e32 v2, vcc, 0x38000, v0
	s_nop 1
	v_addc_co_u32_e32 v3, vcc, 0, v1, vcc
	v_add_co_u32_e32 v0, vcc, 0x3c000, v0
	s_nop 1
	v_addc_co_u32_e32 v1, vcc, 0, v1, vcc
	global_load_dwordx4 v[4:7], v[2:3], off nt
	s_nop 0
	global_load_dwordx4 v[0:3], v[0:1], off nt
	s_andn2_b64 vcc, exec, s[26:27]
	s_cbranch_vccnz .LBB0_359
	v_lshlrev_b32_e32 v64, 2, v114
	global_load_dword v114, v64, s[48:49]
	s_nop 0
	global_load_dword v64, v113, s[48:49] offset:16
	s_waitcnt vmcnt(0)
	v_pk_mul_f32 v[116:117], v[60:61], v[114:115] op_sel_hi:[1,0]
	v_pk_mul_f32 v[114:115], v[62:63], v[114:115] op_sel_hi:[1,0]
	ds_write2_b32 v88, v116, v117 offset1:1
	ds_write2_b32 v88, v114, v115 offset0:2 offset1:3
	s_cbranch_execnz .LBB0_334
